# v15 plus ssq row-stat loads of the gate-up and Cq GEMM epilogues hoisted above the K loop (removes one memory round trip per unit)
# speedup vs baseline: 1.0106x; 1.0106x over previous
; #define PG8_STAGE(bufoff, gbase, voff) do { _Pragma("unroll") for (int _i = 0; _i < 2; ++_i) \
;         __builtin_amdgcn_global_load_lds((const unsigned*)((const char*)(gbase) + (voff)[_i]), (LAS unsigned*)(lds + (bufoff) + ldsw + _i * 8192), 16, 0, 0); } while (0)
; #define PG8_WAIT_V(n) asm volatile("s_waitcnt vmcnt(" #n ")" ::: "memory")
; #define PG8_BAR __builtin_amdgcn_s_barrier()
;     DI void prep(const Unit& u, int tid) const { if (tid < 256) *(LAS f32x4*)(tbl + (u.ui & 1) * 4096 + tid * 16) = factors(u.r0 + tid); }
; template <class Epi, bool ALIGN_EPI>
; DI void gemm_phase(lptr lds, const Gemm g, const StaticOrder& S, const Epi& E) {
;     ...
;     const char* cA = (const char*)g.A + (size_t)cur.pm * tstepA; const char* cB = (const char*)g.Bt + (size_t)cur.pn * tstepB;
;     if constexpr (Epi::RESCALE) E.prep(cur, tid);
;     PG8_STAGE(PG8_SB(0, 0), cB, voffB); PG8_STAGE(PG8_SB(0, 1), cB + hstepB, voffB); PG8_STAGE(PG8_SA(0, 0), cA, voffA); PG8_STAGE(PG8_SA(0, 1), cA + hstepA, voffA);
;     if (wr == 1) PG8_BAR;
;     PG8_WAIT_V(2); PG8_BAR;
;     PG8_STAGE(PG8_SB(1, 0), cB + kstep, voffB); PG8_STAGE(PG8_SA(1, 0), cA + kstep, voffA); PG8_STAGE(PG8_SB(1, 1), cB + hstepB + kstep, voffB);
;     PG8_WAIT_V(6); PG8_BAR;
;     for (;;) {
;         const bool has_next = S.next(ui + 1, nxt);
;         const char* nA = has_next ? (const char*)g.A + (size_t)nxt.pm * tstepA : cA; const char* nB = has_next ? (const char*)g.Bt + (size_t)nxt.pn * tstepB : cB;
;     template <int NAI> DI void run(AccRef acc, const Unit& u, int wr, int wc, int fr, int fq) const {
;     ...
;             for (int m = 0; m < 4; ++m) rsv[ai][m] = ssq[EPI_ROW(ai, m)];
.LBB0_972:
	s_ashr_i32 s19, s18, 31
	s_lshl_b64 s[20:21], s[18:19], 19
	s_add_u32 s20, s82, s20
	s_addc_u32 s21, s83, s21
	s_and_b64 s[22:23], s[2:3], exec
	s_cselect_b32 s19, s21, s25
	s_cselect_b32 s47, s20, s24
	s_ashr_i32 s17, s16, 31
	s_lshl_b64 s[22:23], s[16:17], 19
	s_add_u32 s22, s0, s22
	s_addc_u32 s23, s1, s23
	s_and_b64 s[28:29], s[2:3], exec
	s_cselect_b32 s17, s23, s27
	s_cselect_b32 s48, s22, s26
	s_add_u32 s24, s24, 0x40080
	s_addc_u32 s25, s25, 0
	s_add_u32 s49, s26, 0x100
	v_mov_b32_e32 v0, 0
	s_addc_u32 s50, s27, 0
	s_mov_b32 s51, -2
	v_mov_b32_e32 v1, v0
	v_mov_b32_e32 v2, v0
	v_mov_b32_e32 v3, v0
	v_mov_b32_e32 v4, v0
	v_mov_b32_e32 v5, v0
	v_mov_b32_e32 v6, v0
	v_mov_b32_e32 v7, v0
	v_mov_b32_e32 v12, v0
	v_mov_b32_e32 v13, v0
	v_mov_b32_e32 v14, v0
	v_mov_b32_e32 v15, v0
	v_mov_b32_e32 v20, v0
	v_mov_b32_e32 v21, v0
	v_mov_b32_e32 v22, v0
	v_mov_b32_e32 v23, v0
	v_mov_b32_e32 v28, v0
	v_mov_b32_e32 v29, v0
	v_mov_b32_e32 v30, v0
	v_mov_b32_e32 v31, v0
	v_mov_b32_e32 v36, v0
	v_mov_b32_e32 v37, v0
	v_mov_b32_e32 v38, v0
	v_mov_b32_e32 v39, v0
	v_mov_b32_e32 v44, v0
	v_mov_b32_e32 v45, v0
	v_mov_b32_e32 v46, v0
	v_mov_b32_e32 v47, v0
	v_mov_b32_e32 v52, v0
	v_mov_b32_e32 v53, v0
	v_mov_b32_e32 v54, v0
	v_mov_b32_e32 v55, v0
	v_mov_b32_e32 v8, v0
	v_mov_b32_e32 v9, v0
	v_mov_b32_e32 v10, v0
	v_mov_b32_e32 v11, v0
	v_mov_b32_e32 v16, v0
	v_mov_b32_e32 v17, v0
	v_mov_b32_e32 v18, v0
	v_mov_b32_e32 v19, v0
	v_mov_b32_e32 v24, v0
	v_mov_b32_e32 v25, v0
	v_mov_b32_e32 v26, v0
	v_mov_b32_e32 v27, v0
	v_mov_b32_e32 v32, v0
	v_mov_b32_e32 v33, v0
	v_mov_b32_e32 v34, v0
	v_mov_b32_e32 v35, v0
	v_mov_b32_e32 v40, v0
	v_mov_b32_e32 v41, v0
	v_mov_b32_e32 v42, v0
	v_mov_b32_e32 v43, v0
	v_mov_b32_e32 v48, v0
	v_mov_b32_e32 v49, v0
	v_mov_b32_e32 v50, v0
	v_mov_b32_e32 v51, v0
	v_mov_b32_e32 v56, v0
	v_mov_b32_e32 v57, v0
	v_mov_b32_e32 v58, v0
	v_mov_b32_e32 v59, v0
	v_mov_b32_e32 v60, v0
	v_mov_b32_e32 v61, v0
	v_mov_b32_e32 v62, v0
	v_mov_b32_e32 v63, v0
	v_mov_b32_e32 v64, v0
	v_mov_b32_e32 v65, v0
	v_mov_b32_e32 v66, v0
	v_mov_b32_e32 v67, v0
	v_mov_b32_e32 v68, v0
	v_mov_b32_e32 v69, v0
	v_mov_b32_e32 v70, v0
	v_mov_b32_e32 v71, v0
	v_mov_b32_e32 v76, v0
	v_mov_b32_e32 v77, v0
	v_mov_b32_e32 v78, v0
	v_mov_b32_e32 v79, v0
	v_mov_b32_e32 v84, v0
	v_mov_b32_e32 v85, v0
	v_mov_b32_e32 v86, v0
	v_mov_b32_e32 v87, v0
	v_mov_b32_e32 v92, v0
	v_mov_b32_e32 v93, v0
	v_mov_b32_e32 v94, v0
	v_mov_b32_e32 v95, v0
	v_mov_b32_e32 v100, v0
	v_mov_b32_e32 v101, v0
	v_mov_b32_e32 v102, v0
	v_mov_b32_e32 v103, v0
	v_mov_b32_e32 v104, v0
	v_mov_b32_e32 v105, v0
	v_mov_b32_e32 v106, v0
	v_mov_b32_e32 v107, v0
	v_mov_b32_e32 v108, v0
	v_mov_b32_e32 v109, v0
	v_mov_b32_e32 v110, v0
	v_mov_b32_e32 v111, v0
	v_mov_b32_e32 v72, v0
	v_mov_b32_e32 v73, v0
	v_mov_b32_e32 v74, v0
	v_mov_b32_e32 v75, v0
	v_mov_b32_e32 v80, v0
	v_mov_b32_e32 v81, v0
	v_mov_b32_e32 v82, v0
	v_mov_b32_e32 v83, v0
	v_mov_b32_e32 v88, v0
	v_mov_b32_e32 v89, v0
	v_mov_b32_e32 v90, v0
	v_mov_b32_e32 v91, v0
	v_mov_b32_e32 v96, v0
	v_mov_b32_e32 v97, v0
	v_mov_b32_e32 v98, v0
	v_mov_b32_e32 v99, v0
	v_mov_b32_e32 v112, v0
	v_mov_b32_e32 v113, v0
	v_mov_b32_e32 v114, v0
	v_mov_b32_e32 v115, v0
	v_mov_b32_e32 v116, v0
	v_mov_b32_e32 v117, v0
	v_mov_b32_e32 v118, v0
	v_mov_b32_e32 v119, v0
	v_mov_b32_e32 v120, v0
	v_mov_b32_e32 v121, v0
	v_mov_b32_e32 v122, v0
	v_mov_b32_e32 v123, v0
	v_mov_b32_e32 v124, v0
	v_mov_b32_e32 v125, v0
	v_mov_b32_e32 v126, v0
	v_mov_b32_e32 v127, v0
	v_add_u32_e32 v232, s45, v156
	v_lshlrev_b32_e32 v232, 2, v232
	global_load_dword v233, v232, s[6:7]
	global_load_dword v234, v232, s[6:7] offset:64
	global_load_dword v235, v232, s[6:7] offset:128
	global_load_dword v236, v232, s[6:7] offset:192
	global_load_dword v237, v232, s[6:7] offset:512
	global_load_dword v238, v232, s[6:7] offset:576
	global_load_dword v239, v232, s[6:7] offset:640
	global_load_dword v240, v232, s[6:7] offset:704

; DI void st8(bf16_t* p, f32x4 a, f32x4 b) { u32x4 w; w.x = cvt_pk_bf16(a.x, a.y); w.y = cvt_pk_bf16(a.z, a.w); w.z = cvt_pk_bf16(b.x, b.y); w.w = cvt_pk_bf16(b.z, b.w); *(u32x4*)p = w; }
;     template <int NAI> DI void run(AccRef acc, const Unit& u, int wr, int wc, int fr, int fq) const {
;         const int cl = u.pn * 256 + wc * 32 + fq * 8;
;         float rsv[2][4];
; #pragma unroll
;         for (int ai = 0; ai < NAI; ++ai)
; #pragma unroll
;             for (int m = 0; m < 4; ++m) rsv[ai][m] = ssq[EPI_ROW(ai, m)];
; #pragma unroll
;         for (int ai = 0; ai < NAI; ++ai)
; #pragma unroll
;             for (int m = 0; m < 4; ++m) {
;                 const int row = EPI_ROW(ai, m); const float rs = 0.0625f * __builtin_amdgcn_rsqf(rsv[ai][m] * (1.f / DM) + EPS);
; #pragma unroll
;                 for (int bj = 0; bj < 2; ++bj) st8(P + G_RK + (size_t)row * 1024 + cl + bj * 128, acc[ai][bj][m][0] * rs, acc[ai][bj][m][1] * rs);
;             }
.LBB0_976:
	v_add_u32_e32 v144, s45, v156
	v_ashrrev_i32_e32 v145, 31, v144
	v_add_u32_e32 v166, 16, v144
	v_lshl_add_u64 v[146:147], v[144:145], 2, s[6:7]
	v_ashrrev_i32_e32 v167, 31, v166
	v_add_u32_e32 v170, 32, v144
	v_mov_b32_e32 v169, v233
	v_lshl_add_u64 v[146:147], v[166:167], 2, s[6:7]
	v_ashrrev_i32_e32 v171, 31, v170
	v_lshl_add_u64 v[148:149], v[170:171], 2, s[6:7]
	v_mov_b32_e32 v188, v234
	v_mov_b32_e32 v189, v235
	v_lshl_or_b32 v172, s46, 8, v158
	v_add_u32_e32 v174, 48, v144
	v_add_u32_e32 v146, 0xb0, v144
	v_add_u32_e32 v154, 0x80, v144
	v_add_u32_e32 v150, 0x90, v144
	v_add_u32_e32 v148, 0xa0, v144
	v_ashrrev_i32_e32 v173, 31, v172
	v_ashrrev_i32_e32 v175, 31, v174
	v_ashrrev_i32_e32 v147, 31, v146
	v_ashrrev_i32_e32 v155, 31, v154
	v_ashrrev_i32_e32 v151, 31, v150
	v_ashrrev_i32_e32 v149, 31, v148
	v_lshlrev_b64 v[176:177], 11, v[144:145]
	v_lshlrev_b64 v[144:145], 1, v[172:173]
	v_lshl_add_u64 v[172:173], v[174:175], 2, s[6:7]
	v_lshl_add_u64 v[184:185], v[146:147], 2, s[6:7]
	v_lshl_add_u64 v[178:179], v[154:155], 2, s[6:7]
	v_lshl_add_u64 v[180:181], v[150:151], 2, s[6:7]
	v_lshl_add_u64 v[182:183], v[148:149], 2, s[6:7]
	v_mov_b32_e32 v190, v236
	v_mov_b32_e32 v191, v237
	v_mov_b32_e32 v192, v238
	v_mov_b32_e32 v193, v239
	s_nop 0
	v_mov_b32_e32 v185, v240
	v_lshl_add_u64 v[186:187], s[14:15], 0, v[176:177]
	v_lshl_add_u64 v[176:177], s[82:83], 0, v[176:177]
	v_lshlrev_b64 v[166:167], 11, v[166:167]
	v_lshl_add_u64 v[176:177], v[176:177], 0, v[144:145]
	v_lshl_add_u64 v[172:173], v[186:187], 0, v[144:145]
	v_lshl_add_u64 v[178:179], s[14:15], 0, v[166:167]
	v_lshl_add_u64 v[166:167], s[82:83], 0, v[166:167]
	v_add_co_u32_e32 v176, vcc, s43, v176
	v_lshl_add_u64 v[178:179], v[178:179], 0, v[144:145]
	s_nop 0
	v_addc_co_u32_e32 v177, vcc, 0, v177, vcc
	v_lshl_add_u64 v[166:167], v[166:167], 0, v[144:145]
	v_fmamk_f32 v169, v169, 0x3a800000, v165
	v_rsq_f32_e32 v169, v169
	v_fmamk_f32 v180, v188, 0x3a800000, v165
	v_rsq_f32_e32 v184, v180
	v_fmamk_f32 v181, v189, 0x3a800000, v165
	v_mul_f32_e32 v180, 0x3d800000, v169
	v_rsq_f32_e32 v186, v181
	v_mul_f32_e32 v184, 0x3d800000, v184
	v_pk_mul_f32 v[126:127], v[126:127], v[180:181] op_sel_hi:[1,0]
	v_pk_mul_f32 v[124:125], v[124:125], v[180:181] op_sel_hi:[1,0]
	v_pk_mul_f32 v[122:123], v[122:123], v[180:181] op_sel_hi:[1,0]
	v_pk_mul_f32 v[120:121], v[120:121], v[180:181] op_sel_hi:[1,0]
	v_pk_mul_f32 v[110:111], v[110:111], v[180:181] op_sel_hi:[1,0]
	v_pk_mul_f32 v[108:109], v[108:109], v[180:181] op_sel_hi:[1,0]
	v_pk_mul_f32 v[182:183], v[106:107], v[180:181] op_sel_hi:[1,0]
	v_pk_mul_f32 v[180:181], v[104:105], v[180:181] op_sel_hi:[1,0]
	v_cvt_pk_bf16_f32 v104, v124, v125
	v_cvt_pk_bf16_f32 v105, v126, v127
	v_cvt_pk_bf16_f32 v106, v120, v121
	v_cvt_pk_bf16_f32 v107, v122, v123
	v_cvt_pk_bf16_f32 v108, v108, v109
	v_cvt_pk_bf16_f32 v109, v110, v111
	v_cvt_pk_bf16_f32 v110, v180, v181
	v_pk_mul_f32 v[118:119], v[118:119], v[184:185] op_sel_hi:[1,0]
	v_pk_mul_f32 v[116:117], v[116:117], v[184:185] op_sel_hi:[1,0]
	v_pk_mul_f32 v[114:115], v[114:115], v[184:185] op_sel_hi:[1,0]
	v_pk_mul_f32 v[112:113], v[112:113], v[184:185] op_sel_hi:[1,0]
	v_pk_mul_f32 v[120:121], v[94:95], v[184:185] op_sel_hi:[1,0]
	v_pk_mul_f32 v[122:123], v[92:93], v[184:185] op_sel_hi:[1,0]
	v_cvt_pk_bf16_f32 v92, v116, v117
	v_cvt_pk_bf16_f32 v93, v118, v119
	v_cvt_pk_bf16_f32 v94, v112, v113
	v_cvt_pk_bf16_f32 v95, v114, v115
	v_cvt_pk_bf16_f32 v111, v182, v183
	v_pk_mul_f32 v[102:103], v[102:103], v[184:185] op_sel_hi:[1,0]
	v_pk_mul_f32 v[100:101], v[100:101], v[184:185] op_sel_hi:[1,0]
	global_store_dwordx4 v[172:173], v[104:107], off
	global_store_dwordx4 v[176:177], v[108:111], off offset:256
	global_store_dwordx4 v[178:179], v[92:95], off
	v_cvt_pk_bf16_f32 v100, v100, v101
	v_cvt_pk_bf16_f32 v101, v102, v103
	v_add_co_u32_e32 v92, vcc, s43, v166
	v_cvt_pk_bf16_f32 v102, v122, v123
	v_cvt_pk_bf16_f32 v103, v120, v121
	v_addc_co_u32_e32 v93, vcc, 0, v167, vcc
	global_store_dwordx4 v[92:93], v[100:103], off offset:256
	v_mul_f32_e32 v92, 0x3d800000, v186
	v_lshlrev_b64 v[94:95], 11, v[170:171]
	v_lshl_add_u64 v[100:101], s[14:15], 0, v[94:95]
	v_pk_mul_f32 v[98:99], v[98:99], v[92:93] op_sel_hi:[1,0]
	v_pk_mul_f32 v[96:97], v[96:97], v[92:93] op_sel_hi:[1,0]
	v_pk_mul_f32 v[102:103], v[90:91], v[92:93] op_sel_hi:[1,0]
	v_pk_mul_f32 v[90:91], v[88:89], v[92:93] op_sel_hi:[1,0]
	v_lshl_add_u64 v[100:101], v[100:101], 0, v[144:145]
	v_cvt_pk_bf16_f32 v88, v96, v97
	v_cvt_pk_bf16_f32 v89, v98, v99
	v_cvt_pk_bf16_f32 v90, v90, v91
	v_cvt_pk_bf16_f32 v91, v102, v103
	v_pk_mul_f32 v[84:85], v[84:85], v[92:93] op_sel_hi:[1,0]
	global_store_dwordx4 v[100:101], v[88:91], off
	v_pk_mul_f32 v[86:87], v[86:87], v[92:93] op_sel_hi:[1,0]
	s_nop 0
	v_pk_mul_f32 v[90:91], v[78:79], v[92:93] op_sel_hi:[1,0]
	v_pk_mul_f32 v[78:79], v[76:77], v[92:93] op_sel_hi:[1,0]
	v_cvt_pk_bf16_f32 v76, v84, v85
	v_fmamk_f32 v84, v190, 0x3a800000, v165
	v_lshl_add_u64 v[88:89], s[82:83], 0, v[94:95]
	v_cvt_pk_bf16_f32 v77, v86, v87
	v_rsq_f32_e32 v86, v84
	v_lshl_add_u64 v[88:89], v[88:89], 0, v[144:145]
	v_add_co_u32_e32 v84, vcc, s43, v88
	v_cvt_pk_bf16_f32 v78, v78, v79
	v_cvt_pk_bf16_f32 v79, v90, v91
	v_addc_co_u32_e32 v85, vcc, 0, v89, vcc
	global_store_dwordx4 v[84:85], v[76:79], off offset:256
	s_nop 1
	v_mul_f32_e32 v76, 0x3d800000, v86
	v_lshlrev_b64 v[78:79], 11, v[174:175]
	v_lshl_add_u64 v[84:85], s[14:15], 0, v[78:79]
	v_pk_mul_f32 v[82:83], v[82:83], v[76:77] op_sel_hi:[1,0]
	v_pk_mul_f32 v[80:81], v[80:81], v[76:77] op_sel_hi:[1,0]
	v_pk_mul_f32 v[86:87], v[74:75], v[76:77] op_sel_hi:[1,0]
; DI void st8(bf16_t* p, f32x4 a, f32x4 b) { u32x4 w; w.x = cvt_pk_bf16(a.x, a.y); w.y = cvt_pk_bf16(a.z, a.w); w.z = cvt_pk_bf16(b.x, b.y); w.w = cvt_pk_bf16(b.z, b.w); *(u32x4*)p = w; }
; #define PG8_BAR __builtin_amdgcn_s_barrier()
;     DI void prep(const Unit& u, int tid) const { if (tid < 256) *(LAS f32x4*)(tbl + (u.ui & 1) * 4096 + tid * 16) = factors(u.r0 + tid); }
; template <class Epi, bool ALIGN_EPI>
; DI void gemm_phase(lptr lds, const Gemm g, const StaticOrder& S, const Epi& E) {
;     ...
;         if (!has_next) break;
; #pragma unroll
;         for (int a = 0; a < 2; ++a)
; #pragma unroll
;             for (int b = 0; b < 2; ++b)
; #pragma unroll
;                 for (int m = 0; m < 4; ++m)
; #pragma unroll
;                     for (int n = 0; n < 2; ++n) acc[a][b][m][n] = (f32x4){0.f, 0.f, 0.f, 0.f};
;         cur = nxt; cA = nA; cB = nB; ++ui;
;         if constexpr (Epi::RESCALE) E.prep(cur, tid);
;         if constexpr (ALIGN_EPI) { if (wr == 1) PG8_BAR; }
;     template <int NAI> DI void run(AccRef acc, const Unit& u, int wr, int wc, int fr, int fq) const {
;     ...
;             for (int m = 0; m < 4; ++m) rsv[ai][m] = ssq[EPI_ROW(ai, m)];
; #pragma unroll
;         for (int ai = 0; ai < NAI; ++ai)
; #pragma unroll
;             for (int m = 0; m < 4; ++m) {
;                 const int row = EPI_ROW(ai, m); const float rs = 0.0625f * __builtin_amdgcn_rsqf(rsv[ai][m] * (1.f / DM) + EPS);
; #pragma unroll
;                 for (int bj = 0; bj < 2; ++bj) st8(P + G_RK + (size_t)row * 1024 + cl + bj * 128, acc[ai][bj][m][0] * rs, acc[ai][bj][m][1] * rs);
;             }
	v_pk_mul_f32 v[74:75], v[72:73], v[76:77] op_sel_hi:[1,0]
	v_lshl_add_u64 v[84:85], v[84:85], 0, v[144:145]
	v_cvt_pk_bf16_f32 v72, v80, v81
	v_cvt_pk_bf16_f32 v73, v82, v83
	v_cvt_pk_bf16_f32 v74, v74, v75
	v_cvt_pk_bf16_f32 v75, v86, v87
	v_pk_mul_f32 v[68:69], v[68:69], v[76:77] op_sel_hi:[1,0]
	global_store_dwordx4 v[84:85], v[72:75], off
	v_pk_mul_f32 v[70:71], v[70:71], v[76:77] op_sel_hi:[1,0]
	s_nop 0
	v_pk_mul_f32 v[74:75], v[66:67], v[76:77] op_sel_hi:[1,0]
	v_pk_mul_f32 v[66:67], v[64:65], v[76:77] op_sel_hi:[1,0]
	v_cvt_pk_bf16_f32 v64, v68, v69
	v_fmamk_f32 v68, v191, 0x3a800000, v165
	v_lshl_add_u64 v[72:73], s[82:83], 0, v[78:79]
	v_cvt_pk_bf16_f32 v65, v70, v71
	v_rsq_f32_e32 v70, v68
	v_lshl_add_u64 v[72:73], v[72:73], 0, v[144:145]
	v_add_co_u32_e32 v68, vcc, s43, v72
	v_cvt_pk_bf16_f32 v66, v66, v67
	v_cvt_pk_bf16_f32 v67, v74, v75
	v_addc_co_u32_e32 v69, vcc, 0, v73, vcc
	global_store_dwordx4 v[68:69], v[64:67], off offset:256
	s_nop 1
	v_mul_f32_e32 v64, 0x3d800000, v70
	v_lshlrev_b64 v[66:67], 11, v[154:155]
	v_lshl_add_u64 v[68:69], s[14:15], 0, v[66:67]
	v_pk_mul_f32 v[62:63], v[62:63], v[64:65] op_sel_hi:[1,0]
	v_pk_mul_f32 v[60:61], v[60:61], v[64:65] op_sel_hi:[1,0]
	v_pk_mul_f32 v[70:71], v[58:59], v[64:65] op_sel_hi:[1,0]
	v_pk_mul_f32 v[58:59], v[56:57], v[64:65] op_sel_hi:[1,0]
	v_lshl_add_u64 v[68:69], v[68:69], 0, v[144:145]
	v_cvt_pk_bf16_f32 v56, v60, v61
	v_cvt_pk_bf16_f32 v57, v62, v63
	v_cvt_pk_bf16_f32 v58, v58, v59
	v_cvt_pk_bf16_f32 v59, v70, v71
	v_pk_mul_f32 v[52:53], v[52:53], v[64:65] op_sel_hi:[1,0]
	global_store_dwordx4 v[68:69], v[56:59], off
	v_pk_mul_f32 v[54:55], v[54:55], v[64:65] op_sel_hi:[1,0]
	s_nop 0
	v_pk_mul_f32 v[58:59], v[46:47], v[64:65] op_sel_hi:[1,0]
	v_pk_mul_f32 v[46:47], v[44:45], v[64:65] op_sel_hi:[1,0]
	v_cvt_pk_bf16_f32 v44, v52, v53
	v_fmamk_f32 v52, v192, 0x3a800000, v165
	v_lshl_add_u64 v[56:57], s[82:83], 0, v[66:67]
	v_cvt_pk_bf16_f32 v45, v54, v55
	v_rsq_f32_e32 v54, v52
	v_lshl_add_u64 v[56:57], v[56:57], 0, v[144:145]
	v_add_co_u32_e32 v52, vcc, s43, v56
	v_cvt_pk_bf16_f32 v46, v46, v47
	v_cvt_pk_bf16_f32 v47, v58, v59
	v_addc_co_u32_e32 v53, vcc, 0, v57, vcc
	global_store_dwordx4 v[52:53], v[44:47], off offset:256
	s_nop 1
	v_mul_f32_e32 v44, 0x3d800000, v54
	v_lshlrev_b64 v[46:47], 11, v[150:151]
	v_lshl_add_u64 v[52:53], s[14:15], 0, v[46:47]
	v_pk_mul_f32 v[50:51], v[50:51], v[44:45] op_sel_hi:[1,0]
	v_pk_mul_f32 v[48:49], v[48:49], v[44:45] op_sel_hi:[1,0]
	v_pk_mul_f32 v[54:55], v[42:43], v[44:45] op_sel_hi:[1,0]
	v_pk_mul_f32 v[42:43], v[40:41], v[44:45] op_sel_hi:[1,0]
	v_lshl_add_u64 v[52:53], v[52:53], 0, v[144:145]
	v_cvt_pk_bf16_f32 v40, v48, v49
	v_cvt_pk_bf16_f32 v41, v50, v51
	v_cvt_pk_bf16_f32 v42, v42, v43
	v_cvt_pk_bf16_f32 v43, v54, v55
	v_pk_mul_f32 v[36:37], v[36:37], v[44:45] op_sel_hi:[1,0]
	global_store_dwordx4 v[52:53], v[40:43], off
	v_pk_mul_f32 v[38:39], v[38:39], v[44:45] op_sel_hi:[1,0]
	s_nop 0
	v_pk_mul_f32 v[42:43], v[30:31], v[44:45] op_sel_hi:[1,0]
	v_pk_mul_f32 v[30:31], v[28:29], v[44:45] op_sel_hi:[1,0]
	v_cvt_pk_bf16_f32 v28, v36, v37
	v_fmamk_f32 v36, v193, 0x3a800000, v165
	v_lshl_add_u64 v[40:41], s[82:83], 0, v[46:47]
	v_cvt_pk_bf16_f32 v29, v38, v39
	v_rsq_f32_e32 v38, v36
	v_lshl_add_u64 v[40:41], v[40:41], 0, v[144:145]
	v_add_co_u32_e32 v36, vcc, s43, v40
	v_cvt_pk_bf16_f32 v30, v30, v31
	v_cvt_pk_bf16_f32 v31, v42, v43
	v_addc_co_u32_e32 v37, vcc, 0, v41, vcc
	global_store_dwordx4 v[36:37], v[28:31], off offset:256
	s_nop 1
	v_mul_f32_e32 v28, 0x3d800000, v38
	v_lshlrev_b64 v[30:31], 11, v[148:149]
	v_lshl_add_u64 v[36:37], s[14:15], 0, v[30:31]
	v_pk_mul_f32 v[34:35], v[34:35], v[28:29] op_sel_hi:[1,0]
	v_pk_mul_f32 v[32:33], v[32:33], v[28:29] op_sel_hi:[1,0]
	v_pk_mul_f32 v[38:39], v[26:27], v[28:29] op_sel_hi:[1,0]
	v_pk_mul_f32 v[26:27], v[24:25], v[28:29] op_sel_hi:[1,0]
	v_lshl_add_u64 v[36:37], v[36:37], 0, v[144:145]
	v_cvt_pk_bf16_f32 v24, v32, v33
	v_cvt_pk_bf16_f32 v25, v34, v35
	v_cvt_pk_bf16_f32 v26, v26, v27
	v_cvt_pk_bf16_f32 v27, v38, v39
	v_pk_mul_f32 v[20:21], v[20:21], v[28:29] op_sel_hi:[1,0]
	global_store_dwordx4 v[36:37], v[24:27], off
	v_pk_mul_f32 v[22:23], v[22:23], v[28:29] op_sel_hi:[1,0]
	s_nop 0
	v_pk_mul_f32 v[26:27], v[14:15], v[28:29] op_sel_hi:[1,0]
	v_pk_mul_f32 v[14:15], v[12:13], v[28:29] op_sel_hi:[1,0]
	v_cvt_pk_bf16_f32 v12, v20, v21
	v_fmamk_f32 v20, v185, 0x3a800000, v165
	v_lshl_add_u64 v[24:25], s[82:83], 0, v[30:31]
	v_cvt_pk_bf16_f32 v13, v22, v23
	v_rsq_f32_e32 v22, v20
	v_lshl_add_u64 v[24:25], v[24:25], 0, v[144:145]
	v_add_co_u32_e32 v20, vcc, s43, v24
	v_cvt_pk_bf16_f32 v14, v14, v15
	v_cvt_pk_bf16_f32 v15, v26, v27
	v_addc_co_u32_e32 v21, vcc, 0, v25, vcc
	global_store_dwordx4 v[20:21], v[12:15], off offset:256
	s_nop 1
	v_mul_f32_e32 v12, 0x3d800000, v22
	v_lshlrev_b64 v[14:15], 11, v[146:147]
	v_lshl_add_u64 v[20:21], s[14:15], 0, v[14:15]
	v_pk_mul_f32 v[18:19], v[18:19], v[12:13] op_sel_hi:[1,0]
	v_pk_mul_f32 v[16:17], v[16:17], v[12:13] op_sel_hi:[1,0]
	v_pk_mul_f32 v[22:23], v[10:11], v[12:13] op_sel_hi:[1,0]
	v_pk_mul_f32 v[10:11], v[8:9], v[12:13] op_sel_hi:[1,0]
	v_lshl_add_u64 v[20:21], v[20:21], 0, v[144:145]
	v_cvt_pk_bf16_f32 v8, v16, v17
	v_cvt_pk_bf16_f32 v9, v18, v19
	v_cvt_pk_bf16_f32 v10, v10, v11
	v_cvt_pk_bf16_f32 v11, v22, v23
	global_store_dwordx4 v[20:21], v[8:11], off
	v_pk_mul_f32 v[4:5], v[4:5], v[12:13] op_sel_hi:[1,0]
	v_pk_mul_f32 v[6:7], v[6:7], v[12:13] op_sel_hi:[1,0]
	v_lshl_add_u64 v[8:9], s[82:83], 0, v[14:15]
	v_lshl_add_u64 v[8:9], v[8:9], 0, v[144:145]
	v_pk_mul_f32 v[10:11], v[2:3], v[12:13] op_sel_hi:[1,0]
	v_pk_mul_f32 v[2:3], v[0:1], v[12:13] op_sel_hi:[1,0]
	v_cvt_pk_bf16_f32 v0, v4, v5
	v_add_co_u32_e32 v4, vcc, 0x8200000, v8
	v_cvt_pk_bf16_f32 v1, v6, v7
	s_nop 0
	v_addc_co_u32_e32 v5, vcc, 0, v9, vcc
	v_cvt_pk_bf16_f32 v2, v2, v3
	v_cvt_pk_bf16_f32 v3, v10, v11
	s_andn2_b64 vcc, exec, s[2:3]
	s_mov_b64 s[2:3], -1
	global_store_dwordx4 v[4:5], v[0:3], off offset:256
	s_cbranch_vccnz .LBB0_965
	s_andn2_b64 vcc, exec, s[8:9]
	s_cbranch_vccnz .LBB0_964
	s_barrier
	s_branch .LBB0_964

; DI void st8(bf16_t* p, f32x4 a, f32x4 b) { u32x4 w; w.x = cvt_pk_bf16(a.x, a.y); w.y = cvt_pk_bf16(a.z, a.w); w.z = cvt_pk_bf16(b.x, b.y); w.w = cvt_pk_bf16(b.z, b.w); *(u32x4*)p = w; }
; DI f32x4 sigm4(f32x4 v) { f32x4 r; r.x = sigm(v.x); r.y = sigm(v.y); r.z = sigm(v.z); r.w = sigm(v.w); return r; }
;     template <int NAI> DI void run(AccRef acc, const Unit& u, int wr, int wc, int fr, int fq) const {
;         const int cl = u.pn * 128 + wc * 32 + fq * 8;
;         float rsv[2][4];
; #pragma unroll
;         for (int ai = 0; ai < NAI; ++ai)
; #pragma unroll
;             for (int m = 0; m < 4; ++m) rsv[ai][m] = ssq[EPI_ROW(ai, m)];
; #pragma unroll
;         for (int ai = 0; ai < NAI; ++ai)
; #pragma unroll
;             for (int m = 0; m < 4; ++m) {
;                 const int row = EPI_ROW(ai, m); const float rs = __builtin_amdgcn_rsqf(rsv[ai][m] * (1.f / DM) + EPS);
;                 const f32x4 g0 = acc[ai][0][m][0] * rs, g1 = acc[ai][0][m][1] * rs, u0 = acc[ai][1][m][0] * rs, u1 = acc[ai][1][m][1] * rs;
;                 st8(P + G_RV + (size_t)row * DFF + cl, g0 * sigm4(g0) * u0, g1 * sigm4(g1) * u1);
;             }
.LBB0_1284:
	v_add_u32_e32 v148, s46, v163
	v_ashrrev_i32_e32 v149, 31, v148
	v_lshl_add_u64 v[144:145], v[148:149], 2, s[6:7]
	v_add_u32_e32 v172, 16, v148
	v_mov_b32_e32 v171, v233
	v_ashrrev_i32_e32 v173, 31, v172
	v_lshl_add_u64 v[144:145], v[172:173], 2, s[6:7]
	v_mov_b32_e32 v173, v234
	v_lshl_or_b32 v174, s47, 7, v165
	v_add_u32_e32 v176, 32, v148
	v_mov_b64_e32 v[144:145], s[14:15]
	v_add_u32_e32 v158, 48, v148
	v_add_u32_e32 v156, 0x80, v148
	v_add_u32_e32 v154, 0x90, v148
	v_add_u32_e32 v150, 0xa0, v148
	v_add_u32_e32 v146, 0xb0, v148
	v_ashrrev_i32_e32 v175, 31, v174
	v_ashrrev_i32_e32 v177, 31, v176
	v_mad_i64_i32 v[178:179], s[24:25], v148, s44, v[144:145]
	v_ashrrev_i32_e32 v159, 31, v158
	v_ashrrev_i32_e32 v157, 31, v156
	v_ashrrev_i32_e32 v155, 31, v154
	v_ashrrev_i32_e32 v151, 31, v150
	v_ashrrev_i32_e32 v147, 31, v146
	v_lshlrev_b64 v[148:149], 1, v[174:175]
	v_lshl_add_u64 v[174:175], v[176:177], 2, s[6:7]
	v_lshl_add_u64 v[180:181], v[158:159], 2, s[6:7]
	v_lshl_add_u64 v[182:183], v[156:157], 2, s[6:7]
	v_lshl_add_u64 v[184:185], v[154:155], 2, s[6:7]
	v_lshl_add_u64 v[186:187], v[150:151], 2, s[6:7]
	v_lshl_add_u64 v[188:189], v[146:147], 2, s[6:7]
	v_mov_b32_e32 v155, v235
	v_mov_b32_e32 v157, v236
	v_mov_b32_e32 v159, v237
	v_mov_b32_e32 v177, v238
	v_mov_b32_e32 v151, v239
	v_mov_b32_e32 v147, v240
	v_lshl_add_u64 v[178:179], v[178:179], 0, v[148:149]
	s_andn2_b64 vcc, exec, s[2:3]
	s_mov_b64 s[2:3], -1
	v_fmamk_f32 v171, v171, 0x3a800000, v170
	v_rsq_f32_e32 v174, v171
	v_fmamk_f32 v171, v173, 0x3a800000, v170
	v_rsq_f32_e32 v180, v171
	v_pk_mul_f32 v[126:127], v[126:127], v[174:175] op_sel_hi:[1,0]
	v_pk_mul_f32 v[124:125], v[124:125], v[174:175] op_sel_hi:[1,0]
	v_pk_mul_f32 v[122:123], v[122:123], v[174:175] op_sel_hi:[1,0]
	v_pk_mul_f32 v[120:121], v[120:121], v[174:175] op_sel_hi:[1,0]
	v_mul_f32_e32 v171, 0xbfb8aa3b, v124
	v_mul_f32_e32 v173, 0xbfb8aa3b, v125
	v_mul_f32_e32 v181, 0xbfb8aa3b, v126
	v_mul_f32_e32 v184, 0xbfb8aa3b, v127
	v_mul_f32_e32 v185, 0xbfb8aa3b, v120
	v_mul_f32_e32 v186, 0xbfb8aa3b, v121
	v_mul_f32_e32 v187, 0xbfb8aa3b, v122
	v_mul_f32_e32 v188, 0xbfb8aa3b, v123
	v_pk_mul_f32 v[108:109], v[108:109], v[174:175] op_sel_hi:[1,0]
	v_pk_mul_f32 v[110:111], v[110:111], v[174:175] op_sel_hi:[1,0]
	v_pk_mul_f32 v[104:105], v[104:105], v[174:175] op_sel_hi:[1,0]
	v_pk_mul_f32 v[106:107], v[106:107], v[174:175] op_sel_hi:[1,0]
	v_pk_mul_f32 v[118:119], v[118:119], v[180:181] op_sel_hi:[1,0]
	v_pk_mul_f32 v[116:117], v[116:117], v[180:181] op_sel_hi:[1,0]
	v_pk_mul_f32 v[114:115], v[114:115], v[180:181] op_sel_hi:[1,0]
	v_pk_mul_f32 v[112:113], v[112:113], v[180:181] op_sel_hi:[1,0]
	v_pk_mul_f32 v[174:175], v[100:101], v[180:181] op_sel_hi:[1,0]
	v_pk_mul_f32 v[182:183], v[102:103], v[180:181] op_sel_hi:[1,0]
	v_pk_mul_f32 v[96:97], v[96:97], v[180:181] op_sel_hi:[1,0]
	v_exp_f32_e32 v100, v171
	v_exp_f32_e32 v101, v173
	v_exp_f32_e32 v102, v181
	v_exp_f32_e32 v103, v184
	v_exp_f32_e32 v171, v185
	v_exp_f32_e32 v173, v186
	v_exp_f32_e32 v181, v187
	v_exp_f32_e32 v184, v188
	v_add_f32_e32 v100, 1.0, v100
	v_add_f32_e32 v101, 1.0, v101
	v_add_f32_e32 v102, 1.0, v102
	v_add_f32_e32 v103, 1.0, v103
	v_add_f32_e32 v171, 1.0, v171
	v_add_f32_e32 v173, 1.0, v173
	v_add_f32_e32 v181, 1.0, v181
	v_add_f32_e32 v187, 1.0, v184
	v_rcp_f32_e32 v100, v100
	v_rcp_f32_e32 v101, v101
	v_rcp_f32_e32 v102, v102
	v_rcp_f32_e32 v103, v103
	v_rcp_f32_e32 v184, v171
	v_rcp_f32_e32 v185, v173
	v_rcp_f32_e32 v186, v181
	v_rcp_f32_e32 v187, v187
	v_pk_mul_f32 v[100:101], v[124:125], v[100:101]
	v_pk_mul_f32 v[102:103], v[126:127], v[102:103]
	v_pk_mul_f32 v[120:121], v[120:121], v[184:185]
	v_pk_mul_f32 v[122:123], v[122:123], v[186:187]
	v_pk_mul_f32 v[102:103], v[110:111], v[102:103]
	v_pk_mul_f32 v[100:101], v[108:109], v[100:101]
	v_pk_mul_f32 v[106:107], v[106:107], v[122:123]
	v_pk_mul_f32 v[104:105], v[104:105], v[120:121]
	v_cvt_pk_bf16_f32 v100, v100, v101
	v_cvt_pk_bf16_f32 v101, v102, v103
	v_cvt_pk_bf16_f32 v102, v104, v105
	v_cvt_pk_bf16_f32 v103, v106, v107
	global_store_dwordx4 v[178:179], v[100:103], off
	v_mul_f32_e32 v106, 0xbfb8aa3b, v112
	v_mul_f32_e32 v107, 0xbfb8aa3b, v113
	v_mul_f32_e32 v102, 0xbfb8aa3b, v116
	v_mul_f32_e32 v103, 0xbfb8aa3b, v117
	v_exp_f32_e32 v102, v102
	v_exp_f32_e32 v103, v103
	v_mul_f32_e32 v108, 0xbfb8aa3b, v114
	v_mul_f32_e32 v109, 0xbfb8aa3b, v115
	v_exp_f32_e32 v106, v106
	v_exp_f32_e32 v107, v107
	v_exp_f32_e32 v108, v108
	v_exp_f32_e32 v109, v109
	v_add_f32_e32 v102, 1.0, v102
	v_add_f32_e32 v103, 1.0, v103
	v_mul_f32_e32 v104, 0xbfb8aa3b, v118
	v_mul_f32_e32 v105, 0xbfb8aa3b, v119
	v_rcp_f32_e32 v102, v102
	v_exp_f32_e32 v104, v104
	v_exp_f32_e32 v105, v105
	v_rcp_f32_e32 v103, v103
	v_add_f32_e32 v106, 1.0, v106
	v_add_f32_e32 v107, 1.0, v107
	v_add_f32_e32 v108, 1.0, v108
	v_add_f32_e32 v109, 1.0, v109
	v_rcp_f32_e32 v106, v106
	v_rcp_f32_e32 v107, v107
	v_rcp_f32_e32 v108, v108
	v_rcp_f32_e32 v109, v109
	v_add_f32_e32 v104, 1.0, v104
	v_add_f32_e32 v105, 1.0, v105
	v_pk_mul_f32 v[102:103], v[116:117], v[102:103]
	v_pk_mul_f32 v[98:99], v[98:99], v[180:181] op_sel_hi:[1,0]
	v_rcp_f32_e32 v104, v104
	v_rcp_f32_e32 v105, v105
	v_pk_mul_f32 v[102:103], v[174:175], v[102:103]
	v_pk_mul_f32 v[106:107], v[112:113], v[106:107]
	v_pk_mul_f32 v[108:109], v[114:115], v[108:109]
	v_pk_mul_f32 v[104:105], v[118:119], v[104:105]
	v_pk_mul_f32 v[108:109], v[98:99], v[108:109]
	v_pk_mul_f32 v[98:99], v[96:97], v[106:107]
	v_cvt_pk_bf16_f32 v96, v102, v103
	v_fmamk_f32 v102, v155, 0x3a800000, v170
	v_rsq_f32_e32 v102, v102
	v_mad_i64_i32 v[100:101], s[24:25], v172, s44, v[144:145]
; DI void st8(bf16_t* p, f32x4 a, f32x4 b) { u32x4 w; w.x = cvt_pk_bf16(a.x, a.y); w.y = cvt_pk_bf16(a.z, a.w); w.z = cvt_pk_bf16(b.x, b.y); w.w = cvt_pk_bf16(b.z, b.w); *(u32x4*)p = w; }
; DI f32x4 sigm4(f32x4 v) { f32x4 r; r.x = sigm(v.x); r.y = sigm(v.y); r.z = sigm(v.z); r.w = sigm(v.w); return r; }
;     template <int NAI> DI void run(AccRef acc, const Unit& u, int wr, int wc, int fr, int fq) const {
;     ...
;         for (int ai = 0; ai < NAI; ++ai)
; #pragma unroll
;             for (int m = 0; m < 4; ++m) {
;                 const int row = EPI_ROW(ai, m); const float rs = __builtin_amdgcn_rsqf(rsv[ai][m] * (1.f / DM) + EPS);
;                 const f32x4 g0 = acc[ai][0][m][0] * rs, g1 = acc[ai][0][m][1] * rs, u0 = acc[ai][1][m][0] * rs, u1 = acc[ai][1][m][1] * rs;
;                 st8(P + G_RV + (size_t)row * DFF + cl, g0 * sigm4(g0) * u0, g1 * sigm4(g1) * u1);
;             }
	v_pk_mul_f32 v[104:105], v[182:183], v[104:105]
	v_lshl_add_u64 v[100:101], v[100:101], 0, v[148:149]
	v_cvt_pk_bf16_f32 v97, v104, v105
	v_cvt_pk_bf16_f32 v98, v98, v99
	v_cvt_pk_bf16_f32 v99, v108, v109
	v_pk_mul_f32 v[94:95], v[94:95], v[102:103] op_sel_hi:[1,0]
	v_pk_mul_f32 v[92:93], v[92:93], v[102:103] op_sel_hi:[1,0]
	global_store_dwordx4 v[100:101], v[96:99], off
	v_mul_f32_e32 v100, 0xbfb8aa3b, v94
	v_mul_f32_e32 v101, 0xbfb8aa3b, v95
	v_mul_f32_e32 v98, 0xbfb8aa3b, v92
	v_mul_f32_e32 v99, 0xbfb8aa3b, v93
	v_exp_f32_e32 v98, v98
	v_exp_f32_e32 v99, v99
	v_exp_f32_e32 v100, v100
	v_exp_f32_e32 v101, v101
	v_add_f32_e32 v98, 1.0, v98
	v_add_f32_e32 v99, 1.0, v99
	v_add_f32_e32 v100, 1.0, v100
	v_add_f32_e32 v101, 1.0, v101
	v_rcp_f32_e32 v98, v98
	v_rcp_f32_e32 v99, v99
	v_rcp_f32_e32 v100, v100
	v_rcp_f32_e32 v101, v101
	v_pk_mul_f32 v[90:91], v[90:91], v[102:103] op_sel_hi:[1,0]
	v_pk_mul_f32 v[88:89], v[88:89], v[102:103] op_sel_hi:[1,0]
	v_pk_mul_f32 v[92:93], v[92:93], v[98:99]
	v_mul_f32_e32 v98, 0xbfb8aa3b, v88
	v_mul_f32_e32 v99, 0xbfb8aa3b, v89
	v_pk_mul_f32 v[94:95], v[94:95], v[100:101]
	v_mul_f32_e32 v100, 0xbfb8aa3b, v90
	v_mul_f32_e32 v101, 0xbfb8aa3b, v91
	v_exp_f32_e32 v98, v98
	v_exp_f32_e32 v99, v99
	v_exp_f32_e32 v100, v100
	v_exp_f32_e32 v101, v101
	v_add_f32_e32 v98, 1.0, v98
	v_add_f32_e32 v99, 1.0, v99
	v_add_f32_e32 v100, 1.0, v100
	v_add_f32_e32 v101, 1.0, v101
	v_rcp_f32_e32 v98, v98
	v_rcp_f32_e32 v99, v99
	v_rcp_f32_e32 v100, v100
	v_rcp_f32_e32 v101, v101
	v_pk_mul_f32 v[84:85], v[84:85], v[102:103] op_sel_hi:[1,0]
	v_pk_mul_f32 v[80:81], v[80:81], v[102:103] op_sel_hi:[1,0]
	v_pk_mul_f32 v[82:83], v[82:83], v[102:103] op_sel_hi:[1,0]
	v_pk_mul_f32 v[84:85], v[84:85], v[92:93]
	v_pk_mul_f32 v[88:89], v[88:89], v[98:99]
	v_pk_mul_f32 v[90:91], v[90:91], v[100:101]
	v_pk_mul_f32 v[86:87], v[86:87], v[102:103] op_sel_hi:[1,0]
	v_pk_mul_f32 v[90:91], v[82:83], v[90:91]
	v_pk_mul_f32 v[82:83], v[80:81], v[88:89]
	v_cvt_pk_bf16_f32 v80, v84, v85
	v_fmamk_f32 v84, v157, 0x3a800000, v170
	v_rsq_f32_e32 v84, v84
	v_mad_i64_i32 v[96:97], s[24:25], v176, s44, v[144:145]
	v_pk_mul_f32 v[86:87], v[86:87], v[94:95]
	v_lshl_add_u64 v[96:97], v[96:97], 0, v[148:149]
	v_cvt_pk_bf16_f32 v81, v86, v87
	v_cvt_pk_bf16_f32 v82, v82, v83
	v_cvt_pk_bf16_f32 v83, v90, v91
	v_pk_mul_f32 v[78:79], v[78:79], v[84:85] op_sel_hi:[1,0]
	v_pk_mul_f32 v[76:77], v[76:77], v[84:85] op_sel_hi:[1,0]
	global_store_dwordx4 v[96:97], v[80:83], off
	v_pk_mul_f32 v[74:75], v[74:75], v[84:85] op_sel_hi:[1,0]
	v_pk_mul_f32 v[72:73], v[72:73], v[84:85] op_sel_hi:[1,0]
	v_pk_mul_f32 v[68:69], v[68:69], v[84:85] op_sel_hi:[1,0]
	v_pk_mul_f32 v[70:71], v[70:71], v[84:85] op_sel_hi:[1,0]
	v_pk_mul_f32 v[64:65], v[64:65], v[84:85] op_sel_hi:[1,0]
	v_pk_mul_f32 v[66:67], v[66:67], v[84:85] op_sel_hi:[1,0]
	v_mul_f32_e32 v82, 0xbfb8aa3b, v76
	v_mul_f32_e32 v83, 0xbfb8aa3b, v77
	v_mul_f32_e32 v84, 0xbfb8aa3b, v78
	v_mul_f32_e32 v85, 0xbfb8aa3b, v79
	v_exp_f32_e32 v82, v82
	v_exp_f32_e32 v83, v83
	v_exp_f32_e32 v84, v84
	v_exp_f32_e32 v85, v85
	v_add_f32_e32 v82, 1.0, v82
	v_add_f32_e32 v83, 1.0, v83
	v_add_f32_e32 v84, 1.0, v84
	v_add_f32_e32 v85, 1.0, v85
	v_rcp_f32_e32 v82, v82
	v_rcp_f32_e32 v83, v83
	v_rcp_f32_e32 v84, v84
	v_rcp_f32_e32 v85, v85
	v_mad_i64_i32 v[80:81], s[24:25], v158, s44, v[144:145]
	v_pk_mul_f32 v[76:77], v[76:77], v[82:83]
	v_mul_f32_e32 v82, 0xbfb8aa3b, v72
	v_mul_f32_e32 v83, 0xbfb8aa3b, v73
	v_pk_mul_f32 v[78:79], v[78:79], v[84:85]
	v_mul_f32_e32 v84, 0xbfb8aa3b, v74
	v_mul_f32_e32 v85, 0xbfb8aa3b, v75
	v_exp_f32_e32 v82, v82
	v_exp_f32_e32 v83, v83
	v_exp_f32_e32 v84, v84
	v_exp_f32_e32 v85, v85
	v_add_f32_e32 v82, 1.0, v82
	v_add_f32_e32 v83, 1.0, v83
	v_add_f32_e32 v84, 1.0, v84
	v_add_f32_e32 v85, 1.0, v85
	v_rcp_f32_e32 v82, v82
	v_rcp_f32_e32 v83, v83
	v_rcp_f32_e32 v84, v84
	v_rcp_f32_e32 v85, v85
	v_pk_mul_f32 v[68:69], v[68:69], v[76:77]
	v_pk_mul_f32 v[72:73], v[72:73], v[82:83]
	v_pk_mul_f32 v[70:71], v[70:71], v[78:79]
	v_pk_mul_f32 v[74:75], v[74:75], v[84:85]
	v_lshl_add_u64 v[80:81], v[80:81], 0, v[148:149]
	v_pk_mul_f32 v[74:75], v[66:67], v[74:75]
	v_pk_mul_f32 v[66:67], v[64:65], v[72:73]
	v_cvt_pk_bf16_f32 v64, v68, v69
	v_fmamk_f32 v68, v159, 0x3a800000, v170
	v_rsq_f32_e32 v68, v68
	v_cvt_pk_bf16_f32 v65, v70, v71
	v_cvt_pk_bf16_f32 v66, v66, v67
	v_cvt_pk_bf16_f32 v67, v74, v75
	v_pk_mul_f32 v[62:63], v[62:63], v[68:69] op_sel_hi:[1,0]
	v_pk_mul_f32 v[60:61], v[60:61], v[68:69] op_sel_hi:[1,0]
	global_store_dwordx4 v[80:81], v[64:67], off
	v_pk_mul_f32 v[58:59], v[58:59], v[68:69] op_sel_hi:[1,0]
	v_pk_mul_f32 v[56:57], v[56:57], v[68:69] op_sel_hi:[1,0]
	v_pk_mul_f32 v[52:53], v[52:53], v[68:69] op_sel_hi:[1,0]
	v_pk_mul_f32 v[54:55], v[54:55], v[68:69] op_sel_hi:[1,0]
	v_pk_mul_f32 v[48:49], v[48:49], v[68:69] op_sel_hi:[1,0]
	v_pk_mul_f32 v[50:51], v[50:51], v[68:69] op_sel_hi:[1,0]
	v_mul_f32_e32 v66, 0xbfb8aa3b, v60
	v_mul_f32_e32 v67, 0xbfb8aa3b, v61
	v_mul_f32_e32 v68, 0xbfb8aa3b, v62
	v_mul_f32_e32 v69, 0xbfb8aa3b, v63
	v_exp_f32_e32 v66, v66
	v_exp_f32_e32 v67, v67
	v_exp_f32_e32 v68, v68
	v_exp_f32_e32 v69, v69
	v_add_f32_e32 v66, 1.0, v66
	v_add_f32_e32 v67, 1.0, v67
	v_add_f32_e32 v68, 1.0, v68
	v_add_f32_e32 v69, 1.0, v69
	v_rcp_f32_e32 v66, v66
	v_rcp_f32_e32 v67, v67
	v_rcp_f32_e32 v68, v68
	v_rcp_f32_e32 v69, v69
	v_mad_i64_i32 v[64:65], s[24:25], v156, s44, v[144:145]
	v_pk_mul_f32 v[60:61], v[60:61], v[66:67]
	v_mul_f32_e32 v66, 0xbfb8aa3b, v56
	v_mul_f32_e32 v67, 0xbfb8aa3b, v57
	v_pk_mul_f32 v[62:63], v[62:63], v[68:69]
	v_mul_f32_e32 v68, 0xbfb8aa3b, v58
	v_mul_f32_e32 v69, 0xbfb8aa3b, v59
; DI void st8(bf16_t* p, f32x4 a, f32x4 b) { u32x4 w; w.x = cvt_pk_bf16(a.x, a.y); w.y = cvt_pk_bf16(a.z, a.w); w.z = cvt_pk_bf16(b.x, b.y); w.w = cvt_pk_bf16(b.z, b.w); *(u32x4*)p = w; }
; DI f32x4 sigm4(f32x4 v) { f32x4 r; r.x = sigm(v.x); r.y = sigm(v.y); r.z = sigm(v.z); r.w = sigm(v.w); return r; }
;     template <int NAI> DI void run(AccRef acc, const Unit& u, int wr, int wc, int fr, int fq) const {
;     ...
;         for (int ai = 0; ai < NAI; ++ai)
; #pragma unroll
;             for (int m = 0; m < 4; ++m) {
;                 const int row = EPI_ROW(ai, m); const float rs = __builtin_amdgcn_rsqf(rsv[ai][m] * (1.f / DM) + EPS);
;                 const f32x4 g0 = acc[ai][0][m][0] * rs, g1 = acc[ai][0][m][1] * rs, u0 = acc[ai][1][m][0] * rs, u1 = acc[ai][1][m][1] * rs;
;                 st8(P + G_RV + (size_t)row * DFF + cl, g0 * sigm4(g0) * u0, g1 * sigm4(g1) * u1);
;             }
	v_exp_f32_e32 v66, v66
	v_exp_f32_e32 v67, v67
	v_exp_f32_e32 v68, v68
	v_exp_f32_e32 v69, v69
	v_add_f32_e32 v66, 1.0, v66
	v_add_f32_e32 v67, 1.0, v67
	v_add_f32_e32 v68, 1.0, v68
	v_add_f32_e32 v69, 1.0, v69
	v_rcp_f32_e32 v66, v66
	v_rcp_f32_e32 v67, v67
	v_rcp_f32_e32 v68, v68
	v_rcp_f32_e32 v69, v69
	v_pk_mul_f32 v[52:53], v[52:53], v[60:61]
	v_pk_mul_f32 v[56:57], v[56:57], v[66:67]
	v_pk_mul_f32 v[54:55], v[54:55], v[62:63]
	v_pk_mul_f32 v[58:59], v[58:59], v[68:69]
	v_lshl_add_u64 v[64:65], v[64:65], 0, v[148:149]
	v_pk_mul_f32 v[58:59], v[50:51], v[58:59]
	v_pk_mul_f32 v[50:51], v[48:49], v[56:57]
	v_cvt_pk_bf16_f32 v48, v52, v53
	v_fmamk_f32 v52, v177, 0x3a800000, v170
	v_rsq_f32_e32 v52, v52
	v_cvt_pk_bf16_f32 v49, v54, v55
	v_cvt_pk_bf16_f32 v50, v50, v51
	v_cvt_pk_bf16_f32 v51, v58, v59
	v_pk_mul_f32 v[46:47], v[46:47], v[52:53] op_sel_hi:[1,0]
	v_pk_mul_f32 v[44:45], v[44:45], v[52:53] op_sel_hi:[1,0]
	global_store_dwordx4 v[64:65], v[48:51], off
	v_pk_mul_f32 v[42:43], v[42:43], v[52:53] op_sel_hi:[1,0]
	v_pk_mul_f32 v[40:41], v[40:41], v[52:53] op_sel_hi:[1,0]
	v_pk_mul_f32 v[36:37], v[36:37], v[52:53] op_sel_hi:[1,0]
	v_pk_mul_f32 v[38:39], v[38:39], v[52:53] op_sel_hi:[1,0]
	v_pk_mul_f32 v[32:33], v[32:33], v[52:53] op_sel_hi:[1,0]
	v_pk_mul_f32 v[34:35], v[34:35], v[52:53] op_sel_hi:[1,0]
	v_mul_f32_e32 v50, 0xbfb8aa3b, v44
	v_mul_f32_e32 v51, 0xbfb8aa3b, v45
	v_mul_f32_e32 v52, 0xbfb8aa3b, v46
	v_mul_f32_e32 v53, 0xbfb8aa3b, v47
	v_exp_f32_e32 v50, v50
	v_exp_f32_e32 v51, v51
	v_exp_f32_e32 v52, v52
	v_exp_f32_e32 v53, v53
	v_add_f32_e32 v50, 1.0, v50
	v_add_f32_e32 v51, 1.0, v51
	v_add_f32_e32 v52, 1.0, v52
	v_add_f32_e32 v53, 1.0, v53
	v_rcp_f32_e32 v50, v50
	v_rcp_f32_e32 v51, v51
	v_rcp_f32_e32 v52, v52
	v_rcp_f32_e32 v53, v53
	v_mad_i64_i32 v[48:49], s[24:25], v154, s44, v[144:145]
	v_pk_mul_f32 v[44:45], v[44:45], v[50:51]
	v_mul_f32_e32 v50, 0xbfb8aa3b, v40
	v_mul_f32_e32 v51, 0xbfb8aa3b, v41
	v_pk_mul_f32 v[46:47], v[46:47], v[52:53]
	v_mul_f32_e32 v52, 0xbfb8aa3b, v42
	v_mul_f32_e32 v53, 0xbfb8aa3b, v43
	v_exp_f32_e32 v50, v50
	v_exp_f32_e32 v51, v51
	v_exp_f32_e32 v52, v52
	v_exp_f32_e32 v53, v53
	v_add_f32_e32 v50, 1.0, v50
	v_add_f32_e32 v51, 1.0, v51
	v_add_f32_e32 v52, 1.0, v52
	v_add_f32_e32 v53, 1.0, v53
	v_rcp_f32_e32 v50, v50
	v_rcp_f32_e32 v51, v51
	v_rcp_f32_e32 v52, v52
	v_rcp_f32_e32 v53, v53
	v_pk_mul_f32 v[36:37], v[36:37], v[44:45]
	v_pk_mul_f32 v[40:41], v[40:41], v[50:51]
	v_pk_mul_f32 v[38:39], v[38:39], v[46:47]
	v_pk_mul_f32 v[42:43], v[42:43], v[52:53]
	v_lshl_add_u64 v[48:49], v[48:49], 0, v[148:149]
	v_pk_mul_f32 v[42:43], v[34:35], v[42:43]
	v_pk_mul_f32 v[34:35], v[32:33], v[40:41]
	v_cvt_pk_bf16_f32 v32, v36, v37
	v_fmamk_f32 v36, v151, 0x3a800000, v170
	v_rsq_f32_e32 v36, v36
	v_cvt_pk_bf16_f32 v33, v38, v39
	v_cvt_pk_bf16_f32 v34, v34, v35
	v_cvt_pk_bf16_f32 v35, v42, v43
	v_pk_mul_f32 v[30:31], v[30:31], v[36:37] op_sel_hi:[1,0]
	v_pk_mul_f32 v[28:29], v[28:29], v[36:37] op_sel_hi:[1,0]
	global_store_dwordx4 v[48:49], v[32:35], off
	v_pk_mul_f32 v[26:27], v[26:27], v[36:37] op_sel_hi:[1,0]
	v_pk_mul_f32 v[24:25], v[24:25], v[36:37] op_sel_hi:[1,0]
	v_pk_mul_f32 v[20:21], v[20:21], v[36:37] op_sel_hi:[1,0]
	v_pk_mul_f32 v[22:23], v[22:23], v[36:37] op_sel_hi:[1,0]
	v_pk_mul_f32 v[16:17], v[16:17], v[36:37] op_sel_hi:[1,0]
	v_pk_mul_f32 v[18:19], v[18:19], v[36:37] op_sel_hi:[1,0]
	v_mul_f32_e32 v34, 0xbfb8aa3b, v28
	v_mul_f32_e32 v35, 0xbfb8aa3b, v29
	v_mul_f32_e32 v36, 0xbfb8aa3b, v30
	v_mul_f32_e32 v37, 0xbfb8aa3b, v31
	v_exp_f32_e32 v34, v34
	v_exp_f32_e32 v35, v35
	v_exp_f32_e32 v36, v36
	v_exp_f32_e32 v37, v37
	v_add_f32_e32 v34, 1.0, v34
	v_add_f32_e32 v35, 1.0, v35
	v_add_f32_e32 v36, 1.0, v36
	v_add_f32_e32 v37, 1.0, v37
	v_rcp_f32_e32 v34, v34
	v_rcp_f32_e32 v35, v35
	v_rcp_f32_e32 v36, v36
	v_rcp_f32_e32 v37, v37
	v_mad_i64_i32 v[32:33], s[24:25], v150, s44, v[144:145]
	v_pk_mul_f32 v[28:29], v[28:29], v[34:35]
	v_mul_f32_e32 v34, 0xbfb8aa3b, v24
	v_mul_f32_e32 v35, 0xbfb8aa3b, v25
	v_pk_mul_f32 v[30:31], v[30:31], v[36:37]
	v_mul_f32_e32 v36, 0xbfb8aa3b, v26
	v_mul_f32_e32 v37, 0xbfb8aa3b, v27
	v_exp_f32_e32 v34, v34
	v_exp_f32_e32 v35, v35
	v_exp_f32_e32 v36, v36
	v_exp_f32_e32 v37, v37
	v_add_f32_e32 v34, 1.0, v34
	v_add_f32_e32 v35, 1.0, v35
	v_add_f32_e32 v36, 1.0, v36
	v_add_f32_e32 v37, 1.0, v37
	v_rcp_f32_e32 v34, v34
	v_rcp_f32_e32 v35, v35
	v_rcp_f32_e32 v36, v36
	v_rcp_f32_e32 v37, v37
	v_pk_mul_f32 v[20:21], v[20:21], v[28:29]
	v_pk_mul_f32 v[24:25], v[24:25], v[34:35]
	v_pk_mul_f32 v[22:23], v[22:23], v[30:31]
	v_pk_mul_f32 v[26:27], v[26:27], v[36:37]
	v_lshl_add_u64 v[32:33], v[32:33], 0, v[148:149]
	v_pk_mul_f32 v[26:27], v[18:19], v[26:27]
	v_pk_mul_f32 v[18:19], v[16:17], v[24:25]
	v_cvt_pk_bf16_f32 v16, v20, v21
	v_fmamk_f32 v20, v147, 0x3a800000, v170
	v_rsq_f32_e32 v20, v20
	v_cvt_pk_bf16_f32 v17, v22, v23
	v_cvt_pk_bf16_f32 v18, v18, v19
	v_cvt_pk_bf16_f32 v19, v26, v27
	v_pk_mul_f32 v[14:15], v[14:15], v[20:21] op_sel_hi:[1,0]
	v_pk_mul_f32 v[12:13], v[12:13], v[20:21] op_sel_hi:[1,0]
	global_store_dwordx4 v[32:33], v[16:19], off
	v_pk_mul_f32 v[10:11], v[10:11], v[20:21] op_sel_hi:[1,0]
	v_pk_mul_f32 v[8:9], v[8:9], v[20:21] op_sel_hi:[1,0]
	v_pk_mul_f32 v[4:5], v[4:5], v[20:21] op_sel_hi:[1,0]
	v_pk_mul_f32 v[6:7], v[6:7], v[20:21] op_sel_hi:[1,0]
	v_pk_mul_f32 v[0:1], v[0:1], v[20:21] op_sel_hi:[1,0]
	v_pk_mul_f32 v[2:3], v[2:3], v[20:21] op_sel_hi:[1,0]
	v_mul_f32_e32 v18, 0xbfb8aa3b, v12
	v_mul_f32_e32 v19, 0xbfb8aa3b, v13
	v_mul_f32_e32 v20, 0xbfb8aa3b, v14
	v_mul_f32_e32 v21, 0xbfb8aa3b, v15
	v_exp_f32_e32 v18, v18
	v_exp_f32_e32 v19, v19
	v_exp_f32_e32 v20, v20
	v_exp_f32_e32 v21, v21
	v_add_f32_e32 v18, 1.0, v18
	v_add_f32_e32 v19, 1.0, v19
	v_add_f32_e32 v20, 1.0, v20
	v_add_f32_e32 v21, 1.0, v21
	v_rcp_f32_e32 v18, v18
	v_rcp_f32_e32 v19, v19
	v_rcp_f32_e32 v20, v20
	v_rcp_f32_e32 v21, v21
	v_mad_i64_i32 v[16:17], s[24:25], v146, s44, v[144:145]
	v_pk_mul_f32 v[12:13], v[12:13], v[18:19]
	v_mul_f32_e32 v18, 0xbfb8aa3b, v8
	v_mul_f32_e32 v19, 0xbfb8aa3b, v9
	v_pk_mul_f32 v[14:15], v[14:15], v[20:21]
	v_mul_f32_e32 v20, 0xbfb8aa3b, v10
	v_mul_f32_e32 v21, 0xbfb8aa3b, v11
	v_exp_f32_e32 v18, v18
	v_exp_f32_e32 v19, v19
	v_exp_f32_e32 v20, v20
	v_exp_f32_e32 v21, v21
	v_add_f32_e32 v18, 1.0, v18
	v_add_f32_e32 v19, 1.0, v19
	v_add_f32_e32 v20, 1.0, v20
	v_add_f32_e32 v21, 1.0, v21
	v_rcp_f32_e32 v18, v18
	v_rcp_f32_e32 v19, v19
	v_rcp_f32_e32 v20, v20
	v_rcp_f32_e32 v21, v21
	v_pk_mul_f32 v[6:7], v[6:7], v[14:15]
	v_pk_mul_f32 v[8:9], v[8:9], v[18:19]
	v_pk_mul_f32 v[4:5], v[4:5], v[12:13]
	v_pk_mul_f32 v[10:11], v[10:11], v[20:21]
	v_lshl_add_u64 v[16:17], v[16:17], 0, v[148:149]
	v_pk_mul_f32 v[10:11], v[2:3], v[10:11]
	v_pk_mul_f32 v[2:3], v[0:1], v[8:9]
	v_cvt_pk_bf16_f32 v0, v4, v5
	v_cvt_pk_bf16_f32 v1, v6, v7
	v_cvt_pk_bf16_f32 v2, v2, v3
	v_cvt_pk_bf16_f32 v3, v10, v11
	global_store_dwordx4 v[16:17], v[0:3], off
	s_cbranch_vccnz .LBB0_1277
; #define PG8_BAR __builtin_amdgcn_s_barrier()
; template <class Epi, bool ALIGN_EPI>
; DI void gemm_phase(lptr lds, const Gemm g, const StaticOrder& S, const Epi& E) {
;     ...
;         if constexpr (ALIGN_EPI) { if (wr == 1) PG8_BAR; }
	s_andn2_b64 vcc, exec, s[8:9]
	s_cbranch_vccnz .LBB0_1276
	s_barrier
	s_branch .LBB0_1276
